# prologue copies (cache shift share + pool-state shift) run by waves 1-7 behind the first grid barrier arrival, overlapping the barrier latency
# speedup vs baseline: 1.0175x; 1.0175x over previous
.LBB0_50:
	s_or_b64 exec, exec, s[0:1]
	s_movk_i32 s0, 0
	v_cmp_gt_i32_e32 vcc, s0, v44
	s_and_saveexec_b64 s[0:1], vcc
	s_cbranch_execz .LBB0_53
	s_add_u32 s4, s66, 0xe05e000
	s_addc_u32 s5, s67, 0
	s_mov_b64 s[6:7], 0
	s_mov_b32 s8, 0x2e8ba2e9
	s_movk_i32 s9, 0xf500
	s_movk_i32 s10, 0x57ff

.LBB0_105:
	s_or_b64 exec, exec, s[4:5]
	s_cmp_eq_u32 s81, 0
	s_cbranch_scc1 .Lb1_skip
	s_mul_i32 s0, s33, 7
	s_add_i32 s0, s0, s81
	s_add_i32 s0, s0, -1
	v_mbcnt_lo_u32_b32 v106, -1, 0
	v_mbcnt_hi_u32_b32 v106, -1, v106
	v_lshlrev_b32_e32 v106, 4, v106
	v_mov_b32_e32 v107, 0x80403
	s_cmpk_lt_u32 s0, 0x160
	s_cbranch_scc0 .Lb1_nops
	s_mul_i32 s1, s0, 0x5d2
	s_lshr_b32 s1, s1, 16
	s_mul_i32 s3, s1, 44
	s_sub_i32 s3, s0, s3
	s_mul_i32 s1, s1, 0xf000
	s_lshl_b32 s3, s3, 10
	s_add_i32 s1, s1, s3
	v_add_u32_e32 v99, s1, v106
	v_add_u32_e32 v100, 0x4000, v99
	v_add_u32_e32 v99, 0xe05e000, v99
	global_load_dwordx4 v[92:95], v100, s[52:53]
.Lb1_nops:
	s_add_i32 s1, s0, 0x18000
	v_mov_b32_e32 v108, s1
	v_min_u32_e32 v101, 0x1feff, v108
	v_add_u32_e32 v108, 0x700, v108
	v_mul_hi_u32 v102, v101, v107
	v_mul_u32_u24_e32 v103, 0x1ff0, v102
	v_and_b32_e32 v104, 7, v102
	v_sub_u32_e32 v103, v101, v103
	v_lshlrev_b32_e32 v104, 23, v104
	v_lshl_add_u32 v103, v103, 10, v104
	v_add_u32_e32 v103, v103, v106
	v_add_u32_e32 v110, 0xa05e000, v103
	v_add_u32_e32 v103, 0x4000, v103
	global_load_dwordx4 v[170:173], v103, s[50:51] nt
	v_min_u32_e32 v101, 0x1feff, v108
	v_add_u32_e32 v108, 0x700, v108
	v_mul_hi_u32 v102, v101, v107
	v_mul_u32_u24_e32 v103, 0x1ff0, v102
	v_and_b32_e32 v104, 7, v102
	v_sub_u32_e32 v103, v101, v103
	v_lshlrev_b32_e32 v104, 23, v104
	v_lshl_add_u32 v103, v103, 10, v104
	v_add_u32_e32 v103, v103, v106
	v_add_u32_e32 v111, 0xa05e000, v103
	v_add_u32_e32 v103, 0x4000, v103
	global_load_dwordx4 v[174:177], v103, s[50:51] nt
	v_min_u32_e32 v101, 0x1feff, v108
	v_add_u32_e32 v108, 0x700, v108
	v_mul_hi_u32 v102, v101, v107
	v_mul_u32_u24_e32 v103, 0x1ff0, v102
	v_and_b32_e32 v104, 7, v102
	v_sub_u32_e32 v103, v101, v103
	v_lshlrev_b32_e32 v104, 23, v104
	v_lshl_add_u32 v103, v103, 10, v104
	v_add_u32_e32 v103, v103, v106
	v_add_u32_e32 v112, 0xa05e000, v103
	v_add_u32_e32 v103, 0x4000, v103
	global_load_dwordx4 v[178:181], v103, s[50:51] nt
	v_min_u32_e32 v101, 0x1feff, v108
	v_add_u32_e32 v108, 0x700, v108
	v_mul_hi_u32 v102, v101, v107
	v_mul_u32_u24_e32 v103, 0x1ff0, v102
	v_and_b32_e32 v104, 7, v102
	v_sub_u32_e32 v103, v101, v103
	v_lshlrev_b32_e32 v104, 23, v104
	v_lshl_add_u32 v103, v103, 10, v104
	v_add_u32_e32 v103, v103, v106
	v_add_u32_e32 v113, 0xa05e000, v103
	v_add_u32_e32 v103, 0x4000, v103
	global_load_dwordx4 v[182:185], v103, s[50:51] nt
	v_min_u32_e32 v101, 0x1feff, v108
	v_add_u32_e32 v108, 0x700, v108
	v_mul_hi_u32 v102, v101, v107
	v_mul_u32_u24_e32 v103, 0x1ff0, v102
	v_and_b32_e32 v104, 7, v102
	v_sub_u32_e32 v103, v101, v103
	v_lshlrev_b32_e32 v104, 23, v104
	v_lshl_add_u32 v103, v103, 10, v104
	v_add_u32_e32 v103, v103, v106
	v_add_u32_e32 v114, 0xa05e000, v103
	v_add_u32_e32 v103, 0x4000, v103
	global_load_dwordx4 v[186:189], v103, s[50:51] nt
	v_min_u32_e32 v101, 0x1feff, v108
	v_add_u32_e32 v108, 0x700, v108
	v_mul_hi_u32 v102, v101, v107
	v_mul_u32_u24_e32 v103, 0x1ff0, v102
	v_and_b32_e32 v104, 7, v102
	v_sub_u32_e32 v103, v101, v103
	v_lshlrev_b32_e32 v104, 23, v104
	v_lshl_add_u32 v103, v103, 10, v104
	v_add_u32_e32 v103, v103, v106
	v_add_u32_e32 v115, 0xa05e000, v103
	v_add_u32_e32 v103, 0x4000, v103
	global_load_dwordx4 v[190:193], v103, s[50:51] nt
	v_min_u32_e32 v101, 0x1feff, v108
	v_add_u32_e32 v108, 0x700, v108
	v_mul_hi_u32 v102, v101, v107
	v_mul_u32_u24_e32 v103, 0x1ff0, v102
	v_and_b32_e32 v104, 7, v102
	v_sub_u32_e32 v103, v101, v103
	v_lshlrev_b32_e32 v104, 23, v104
	v_lshl_add_u32 v103, v103, 10, v104
	v_add_u32_e32 v103, v103, v106
	v_add_u32_e32 v116, 0xa05e000, v103
	v_add_u32_e32 v103, 0x4000, v103
	global_load_dwordx4 v[194:197], v103, s[50:51] nt
	v_min_u32_e32 v101, 0x1feff, v108
	v_add_u32_e32 v108, 0x700, v108
	v_mul_hi_u32 v102, v101, v107
	v_mul_u32_u24_e32 v103, 0x1ff0, v102
	v_and_b32_e32 v104, 7, v102
	v_sub_u32_e32 v103, v101, v103
	v_lshlrev_b32_e32 v104, 23, v104
	v_lshl_add_u32 v103, v103, 10, v104
	v_add_u32_e32 v103, v103, v106
	v_add_u32_e32 v117, 0xa05e000, v103
	v_add_u32_e32 v103, 0x4000, v103
	global_load_dwordx4 v[198:201], v103, s[50:51] nt
	v_min_u32_e32 v101, 0x1feff, v108
	v_add_u32_e32 v108, 0x700, v108
	v_mul_hi_u32 v102, v101, v107
	v_mul_u32_u24_e32 v103, 0x1ff0, v102
	v_and_b32_e32 v104, 7, v102
	v_sub_u32_e32 v103, v101, v103
	v_lshlrev_b32_e32 v104, 23, v104
	v_lshl_add_u32 v103, v103, 10, v104
	v_add_u32_e32 v103, v103, v106
	v_add_u32_e32 v118, 0xa05e000, v103
	v_add_u32_e32 v103, 0x4000, v103
	global_load_dwordx4 v[202:205], v103, s[50:51] nt
	v_min_u32_e32 v101, 0x1feff, v108
	v_add_u32_e32 v108, 0x700, v108
	v_mul_hi_u32 v102, v101, v107
	v_mul_u32_u24_e32 v103, 0x1ff0, v102
	v_and_b32_e32 v104, 7, v102
	v_sub_u32_e32 v103, v101, v103
	v_lshlrev_b32_e32 v104, 23, v104
	v_lshl_add_u32 v103, v103, 10, v104
	v_add_u32_e32 v103, v103, v106
	v_add_u32_e32 v119, 0xa05e000, v103
	v_add_u32_e32 v103, 0x4000, v103
	global_load_dwordx4 v[206:209], v103, s[50:51] nt
	v_min_u32_e32 v101, 0x1feff, v108
	v_add_u32_e32 v108, 0x700, v108
	v_mul_hi_u32 v102, v101, v107
	v_mul_u32_u24_e32 v103, 0x1ff0, v102
	v_and_b32_e32 v104, 7, v102
	v_sub_u32_e32 v103, v101, v103
	v_lshlrev_b32_e32 v104, 23, v104
	v_lshl_add_u32 v103, v103, 10, v104
	v_add_u32_e32 v103, v103, v106
	v_add_u32_e32 v120, 0xa05e000, v103
	v_add_u32_e32 v103, 0x4000, v103
	global_load_dwordx4 v[210:213], v103, s[50:51] nt
	v_min_u32_e32 v101, 0x1feff, v108
	v_add_u32_e32 v108, 0x700, v108
	v_mul_hi_u32 v102, v101, v107
	v_mul_u32_u24_e32 v103, 0x1ff0, v102
	v_and_b32_e32 v104, 7, v102
	v_sub_u32_e32 v103, v101, v103
	v_lshlrev_b32_e32 v104, 23, v104
	v_lshl_add_u32 v103, v103, 10, v104
	v_add_u32_e32 v103, v103, v106
	v_add_u32_e32 v121, 0xa05e000, v103
	v_add_u32_e32 v103, 0x4000, v103
	global_load_dwordx4 v[214:217], v103, s[50:51] nt
	v_min_u32_e32 v101, 0x1feff, v108
	v_add_u32_e32 v108, 0x700, v108
	v_mul_hi_u32 v102, v101, v107
	v_mul_u32_u24_e32 v103, 0x1ff0, v102
	v_and_b32_e32 v104, 7, v102
	v_sub_u32_e32 v103, v101, v103
	v_lshlrev_b32_e32 v104, 23, v104
	v_lshl_add_u32 v103, v103, 10, v104
	v_add_u32_e32 v103, v103, v106
	v_add_u32_e32 v122, 0xa05e000, v103
	v_add_u32_e32 v103, 0x4000, v103
	global_load_dwordx4 v[218:221], v103, s[50:51] nt
	v_min_u32_e32 v101, 0x1feff, v108
	v_add_u32_e32 v108, 0x700, v108
	v_mul_hi_u32 v102, v101, v107
	v_mul_u32_u24_e32 v103, 0x1ff0, v102
	v_and_b32_e32 v104, 7, v102
	v_sub_u32_e32 v103, v101, v103
	v_lshlrev_b32_e32 v104, 23, v104
	v_lshl_add_u32 v103, v103, 10, v104
	v_add_u32_e32 v103, v103, v106
	v_add_u32_e32 v123, 0xa05e000, v103
	v_add_u32_e32 v103, 0x4000, v103
	global_load_dwordx4 v[222:225], v103, s[50:51] nt
	v_min_u32_e32 v101, 0x1feff, v108
	v_add_u32_e32 v108, 0x700, v108
	v_mul_hi_u32 v102, v101, v107
	v_mul_u32_u24_e32 v103, 0x1ff0, v102
	v_and_b32_e32 v104, 7, v102
	v_sub_u32_e32 v103, v101, v103
	v_lshlrev_b32_e32 v104, 23, v104
	v_lshl_add_u32 v103, v103, 10, v104
	v_add_u32_e32 v103, v103, v106
	v_add_u32_e32 v124, 0xa05e000, v103
	v_add_u32_e32 v103, 0x4000, v103
	global_load_dwordx4 v[226:229], v103, s[50:51] nt
	v_min_u32_e32 v101, 0x1feff, v108
	v_add_u32_e32 v108, 0x700, v108
	v_mul_hi_u32 v102, v101, v107
	v_mul_u32_u24_e32 v103, 0x1ff0, v102
	v_and_b32_e32 v104, 7, v102
	v_sub_u32_e32 v103, v101, v103
	v_lshlrev_b32_e32 v104, 23, v104
	v_lshl_add_u32 v103, v103, 10, v104
	v_add_u32_e32 v103, v103, v106
	v_add_u32_e32 v125, 0xa05e000, v103
	v_add_u32_e32 v103, 0x4000, v103
	global_load_dwordx4 v[230:233], v103, s[50:51] nt
	v_min_u32_e32 v101, 0x1feff, v108
	v_add_u32_e32 v108, 0x700, v108
	v_mul_hi_u32 v102, v101, v107
	v_mul_u32_u24_e32 v103, 0x1ff0, v102
	v_and_b32_e32 v104, 7, v102
	v_sub_u32_e32 v103, v101, v103
	v_lshlrev_b32_e32 v104, 23, v104
	v_lshl_add_u32 v103, v103, 10, v104
	v_add_u32_e32 v103, v103, v106
	v_add_u32_e32 v126, 0xa05e000, v103
	v_add_u32_e32 v103, 0x4000, v103
	global_load_dwordx4 v[234:237], v103, s[50:51] nt
	v_min_u32_e32 v101, 0x1feff, v108
	v_add_u32_e32 v108, 0x700, v108
	v_mul_hi_u32 v102, v101, v107
	v_mul_u32_u24_e32 v103, 0x1ff0, v102
	v_and_b32_e32 v104, 7, v102
	v_sub_u32_e32 v103, v101, v103
	v_lshlrev_b32_e32 v104, 23, v104
	v_lshl_add_u32 v103, v103, 10, v104
	v_add_u32_e32 v103, v103, v106
	v_add_u32_e32 v127, 0xa05e000, v103
	v_add_u32_e32 v103, 0x4000, v103
	global_load_dwordx4 v[140:143], v103, s[50:51] nt
	v_min_u32_e32 v101, 0x1feff, v108
	v_add_u32_e32 v108, 0x700, v108
	v_mul_hi_u32 v102, v101, v107
	v_mul_u32_u24_e32 v103, 0x1ff0, v102
	v_and_b32_e32 v104, 7, v102
	v_sub_u32_e32 v103, v101, v103
	v_lshlrev_b32_e32 v104, 23, v104
	v_lshl_add_u32 v103, v103, 10, v104
	v_add_u32_e32 v103, v103, v106
	v_add_u32_e32 v128, 0xa05e000, v103
	v_add_u32_e32 v103, 0x4000, v103
	global_load_dwordx4 v[144:147], v103, s[50:51] nt
	s_waitcnt vmcnt(18)
	global_store_dwordx4 v110, v[170:173], s[66:67] nt
	s_waitcnt vmcnt(18)
	global_store_dwordx4 v111, v[174:177], s[66:67] nt
	s_waitcnt vmcnt(18)
	global_store_dwordx4 v112, v[178:181], s[66:67] nt
	s_waitcnt vmcnt(18)
	global_store_dwordx4 v113, v[182:185], s[66:67] nt
	s_waitcnt vmcnt(18)
	global_store_dwordx4 v114, v[186:189], s[66:67] nt
	s_waitcnt vmcnt(18)
	global_store_dwordx4 v115, v[190:193], s[66:67] nt
	s_waitcnt vmcnt(18)
	global_store_dwordx4 v116, v[194:197], s[66:67] nt
	s_waitcnt vmcnt(18)
	global_store_dwordx4 v117, v[198:201], s[66:67] nt
	s_waitcnt vmcnt(18)
	global_store_dwordx4 v118, v[202:205], s[66:67] nt
	s_waitcnt vmcnt(18)
	global_store_dwordx4 v119, v[206:209], s[66:67] nt
	s_waitcnt vmcnt(18)
	global_store_dwordx4 v120, v[210:213], s[66:67] nt
	s_waitcnt vmcnt(18)
	global_store_dwordx4 v121, v[214:217], s[66:67] nt
	s_waitcnt vmcnt(18)
	global_store_dwordx4 v122, v[218:221], s[66:67] nt
	s_waitcnt vmcnt(18)
	global_store_dwordx4 v123, v[222:225], s[66:67] nt
	s_waitcnt vmcnt(18)
	global_store_dwordx4 v124, v[226:229], s[66:67] nt
	s_waitcnt vmcnt(18)
	global_store_dwordx4 v125, v[230:233], s[66:67] nt
	s_waitcnt vmcnt(18)
	global_store_dwordx4 v126, v[234:237], s[66:67] nt
	s_waitcnt vmcnt(18)
	global_store_dwordx4 v127, v[140:143], s[66:67] nt
	s_waitcnt vmcnt(18)
	global_store_dwordx4 v128, v[144:147], s[66:67] nt
	s_cmpk_lt_u32 s0, 0x160
	s_cbranch_scc0 .Lb1_skip
	global_store_dwordx4 v99, v[92:95], s[66:67]
.Lb1_skip:
	s_add_u32 s28, s92, 0x4600000
	s_addc_u32 s29, s93, 0
	s_cmpk_gt_i32 s2, 0xbf
	s_waitcnt lgkmcnt(0)
	s_barrier
	v_mbcnt_lo_u32_b32 v0, -1, 0
	v_mbcnt_hi_u32_b32 v0, -1, v0
	s_cbranch_scc1 .LBB0_138
	v_add_u32_e32 v4, s97, v0
	v_and_b32_e32 v1, 15, v0
	v_ashrrev_i32_e32 v6, 6, v4
	v_lshlrev_b32_e32 v5, 2, v1
	v_lshlrev_b32_e32 v2, 8, v6
	v_bfe_u32 v7, v0, 4, 2
	v_lshlrev_b32_e32 v6, 12, v6
	v_and_b32_e32 v34, 31, v0
	v_ashrrev_i32_e32 v0, 5, v4
	v_add3_u32 v5, 0, v5, v6
	v_add_u32_e32 v6, 0x2000, v0
	s_movk_i32 s3, 0x3000
	v_mad_i64_i32 v[16:17], s[0:1], v6, s3, 0
	v_ashrrev_i32_e32 v6, 7, v4
	v_and_b32_e32 v0, 3, v0
	v_mul_lo_u32 v9, v6, 15
	v_lshlrev_b32_e32 v6, 11, v6
	s_movk_i32 s4, 0x7fc
	v_add3_u32 v36, v0, v9, 11
	v_or3_b32 v37, v6, v0, s4
	v_add_u32_e32 v0, 0x200, v4
	v_lshl_add_u32 v35, v4, 2, 0
	v_ashrrev_i32_e32 v4, 5, v0
	v_add_u32_e32 v6, 0x2000, v4
	v_ashrrev_i32_e32 v0, 7, v0
	v_lshlrev_b32_e32 v22, 4, v7
	v_mov_b32_e32 v23, 0
	v_ashrrev_i32_e32 v3, 31, v2
	v_lshlrev_b32_e32 v8, 9, v7
	v_mad_i64_i32 v[18:19], s[0:1], v6, s3, 0
	v_and_b32_e32 v4, 3, v4
	v_mul_lo_u32 v6, v0, 15
	v_lshlrev_b32_e32 v0, 11, v0
	s_waitcnt vmcnt(1)
	v_lshl_add_u64 v[24:25], s[92:93], 0, v[22:23]
	v_lshl_or_b32 v22, v1, 12, v22
	v_add3_u32 v38, v4, v6, 11
	v_or3_b32 v39, v0, v4, s4
	v_lshlrev_b64 v[20:21], 1, v[2:3]
	v_lshl_or_b32 v26, s2, 5, v1
	s_lshl_b32 s0, s94, 5
	v_lshl_add_u64 v[28:29], s[92:93], 0, v[22:23]
	s_mov_b64 s[4:5], 0x100
	v_add_u32_e32 v40, v5, v8
	s_movk_i32 s1, 0x7fff
	s_mov_b32 s3, s2
	s_branch .LBB0_108
